# pvprio_s + up K-loop: leading wave group's counted vmcnt waits moved from the end of its load phase to the end of the following MMA phase (one more slot of DMA latency slack)
# baseline (speedup 1.0000x reference)
; #define PG8_STAGE(bufoff, gbase, voff) glds16s2((voff)[0], (voff)[1], (const void*)(gbase), ldsn + (unsigned)(bufoff))
; #define PG8_LDA(dst, b, h) do { _Pragma("unroll") for (int m = 0; m < 4; ++m) _Pragma("unroll") for (int k = 0; k < 2; ++k) dst[m][k] = *(const LAS bf16x8*)(lds + PG8_SA(b, h) + aoff + m * 2048 + k * 1024); } while (0)
; #define PG8_LDB(dst, b, h) do { _Pragma("unroll") for (int n = 0; n < 2; ++n) _Pragma("unroll") for (int k = 0; k < 2; ++k) dst[n][k] = *(const LAS bf16x8*)(lds + PG8_SB(b, h) + boff + n * 2048 + k * 1024); } while (0)
; #define PG8_MMA(ai, bj, At, Bt) do { __builtin_amdgcn_s_setprio(1); _Pragma("unroll") for (int m = 0; m < 4; ++m) _Pragma("unroll") for (int n = 0; n < 2; ++n) _Pragma("unroll") for (int k = 0; k < 2; ++k) \
;         acc[ai][bj][m][n] = __builtin_amdgcn_mfma_f32_16x16x32_bf16(Bt[n][k], At[m][k], acc[ai][bj][m][n], 0, 0, 0); __builtin_amdgcn_s_setprio(0); } while (0)
; #define PG8_WAIT_V(n) asm volatile("s_waitcnt vmcnt(" #n ")" ::: "memory")
; #define PG8_WAIT_L(n) asm volatile("s_waitcnt lgkmcnt(" #n ")" ::: "memory")
; #define PG8_BAR __builtin_amdgcn_s_barrier()
; #define PG8_SCHED __builtin_amdgcn_sched_barrier(0)
; template <class Epi, bool ALIGN_EPI, bool EARLY_DRAIN = true, class Pre = NoPre>
; __device__ __forceinline__ void gemm_phase(LAS unsigned char* lds, const Gemm g, const StaticOrder& S, const Epi& E, int wv, const Pre& pre = Pre()) {
;     ...
;             PG8_WAIT_L(0); PG8_BAR; PG8_MMA(0, 0, At, B0); PG8_MMA(0, 1, At, B1); PG8_BAR; PG8_SCHED;
;             PG8_LDA(At, 0, 1); PG8_STAGE(PG8_SB(0, 0), b2, voffB); PG8_STAGE(PG8_SB(0, 1), b2 + bhs, voffB); PG8_STAGE(PG8_SA(0, 0), a2, voffA);
;             if (!lf_) PG8_WAIT_V(8);
;             PG8_WAIT_L(0); PG8_BAR; PG8_MMA(1, 0, At, B0); PG8_MMA(1, 1, At, B1); PG8_BAR; PG8_SCHED;
;             PG8_LDB(B0, 1, 0); PG8_LDB(B1, 1, 1); PG8_SCHED; PG8_LDA(At, 1, 0); PG8_STAGE(PG8_SA(0, 1), a2 + ahs, voffA);
;             if (!lf_) PG8_WAIT_V(8);
;             PG8_WAIT_L(0); PG8_BAR; PG8_MMA(0, 0, At, B0); PG8_MMA(0, 1, At, B1); PG8_BAR; PG8_SCHED;
;             PG8_LDA(At, 1, 1); PG8_STAGE(PG8_SB(1, 0), b3, voffB); PG8_STAGE(PG8_SB(1, 1), b3 + bhs, voffB); PG8_STAGE(PG8_SA(1, 0), a3, voffA);
;             PG8_WAIT_V(8); PG8_WAIT_L(0); PG8_BAR; PG8_MMA(1, 0, At, B0); PG8_MMA(1, 1, At, B1); PG8_BAR; PG8_SCHED;
.LBB0_558:
	s_add_u32 s14, s86, 0x80
	s_waitcnt lgkmcnt(0)
	s_addc_u32 s15, s87, 0
	s_add_u32 s40, s84, 0x80
	s_addc_u32 s41, s85, 0
	s_barrier
	s_setprio 1
	v_mfma_f32_16x16x32_bf16 v[78:81], v[178:181], v[154:157], v[78:81]
	v_mfma_f32_16x16x32_bf16 v[146:149], v[182:185], v[202:205], v[78:81]
	v_mfma_f32_16x16x32_bf16 v[78:81], v[178:181], v[126:129], v[92:95]
	v_mfma_f32_16x16x32_bf16 v[70:73], v[162:165], v[154:157], v[70:73]
	v_mfma_f32_16x16x32_bf16 v[74:77], v[162:165], v[126:129], v[74:77]
	v_mfma_f32_16x16x32_bf16 v[150:153], v[182:185], v[158:161], v[78:81]
	v_mfma_f32_16x16x32_bf16 v[78:81], v[162:165], v[194:197], v[82:85]
	v_mfma_f32_16x16x32_bf16 v[66:69], v[178:181], v[194:197], v[66:69]
	v_mfma_f32_16x16x32_bf16 v[54:57], v[162:165], v[186:189], v[54:57]
	v_mfma_f32_16x16x32_bf16 v[50:53], v[178:181], v[186:189], v[50:53]
	v_mfma_f32_16x16x32_bf16 v[70:73], v[174:177], v[202:205], v[70:73]
	v_mfma_f32_16x16x32_bf16 v[74:77], v[174:177], v[158:161], v[74:77]
	v_mfma_f32_16x16x32_bf16 v[82:85], v[174:177], v[198:201], v[78:81]
	v_mfma_f32_16x16x32_bf16 v[66:69], v[182:185], v[198:201], v[66:69]
	v_mfma_f32_16x16x32_bf16 v[54:57], v[174:177], v[190:193], v[54:57]
	v_mfma_f32_16x16x32_bf16 v[50:53], v[182:185], v[190:193], v[50:53]
	s_setprio 0
	s_setprio 1
	v_mfma_f32_16x16x32_bf16 v[78:81], v[138:141], v[154:157], v[86:89]
	v_mfma_f32_16x16x32_bf16 v[88:91], v[142:145], v[202:205], v[78:81]
	v_mfma_f32_16x16x32_bf16 v[78:81], v[166:169], v[154:157], v[102:105]
	v_mfma_f32_16x16x32_bf16 v[154:157], v[170:173], v[202:205], v[78:81]
	v_mfma_f32_16x16x32_bf16 v[78:81], v[138:141], v[126:129], v[96:99]
	v_mfma_f32_16x16x32_bf16 v[98:101], v[142:145], v[158:161], v[78:81]
	v_mfma_f32_16x16x32_bf16 v[78:81], v[166:169], v[126:129], v[118:121]
	v_mfma_f32_16x16x32_bf16 v[158:161], v[170:173], v[158:161], v[78:81]
	v_mfma_f32_16x16x32_bf16 v[78:81], v[138:141], v[194:197], v[122:125]
	v_mfma_f32_16x16x32_bf16 v[126:129], v[142:145], v[198:201], v[78:81]
	v_mfma_f32_16x16x32_bf16 v[78:81], v[166:169], v[194:197], v[110:113]
	v_mfma_f32_16x16x32_bf16 v[62:65], v[138:141], v[186:189], v[62:65]
	v_mfma_f32_16x16x32_bf16 v[58:61], v[166:169], v[186:189], v[58:61]
	v_mfma_f32_16x16x32_bf16 v[110:113], v[170:173], v[198:201], v[78:81]
	v_mfma_f32_16x16x32_bf16 v[62:65], v[142:145], v[190:193], v[62:65]
	v_mfma_f32_16x16x32_bf16 v[58:61], v[170:173], v[190:193], v[58:61]
	s_setprio 0
	s_cmp_eq_u32 s18, 0
	s_cbranch_scc1 .Llw_up_m3
	s_waitcnt vmcnt(8)
.Llw_up_m3:
	s_barrier
	s_nop 0
	ds_read_b128 v[78:81], v245 offset:49152
	ds_read_b128 v[92:95], v245 offset:50176
	ds_read_b128 v[102:105], v245 offset:51200
	ds_read_b128 v[118:121], v245 offset:52224
	ds_read_b128 v[122:125], v245 offset:53248
	ds_read_b128 v[186:189], v245 offset:54272
	ds_read_b128 v[190:193], v245 offset:55296
	ds_read_b128 v[194:197], v245 offset:56320
	s_mov_b32 m0, s64
	s_nop 0
	global_load_lds_dwordx4 v251, s[40:41]
	s_add_u32 m0, m0, 0x2000
	s_nop 0
	global_load_lds_dwordx4 v247, s[40:41]
	s_add_u32 s40, s84, 0x580080
	s_addc_u32 s41, s85, 0
	s_mov_b32 m0, s66
	s_nop 0
	global_load_lds_dwordx4 v251, s[40:41]
	s_add_u32 m0, m0, 0x2000
	s_nop 0
	global_load_lds_dwordx4 v247, s[40:41]
	s_nop 0
	s_mov_b32 m0, s65
	s_nop 0
	global_load_lds_dwordx4 v250, s[14:15]
	s_add_u32 m0, m0, 0x2000
	s_nop 0
	global_load_lds_dwordx4 v246, s[14:15]
	s_cmp_lg_u32 s18, 0
	s_cbranch_scc1 .Llw_up_s0
	s_waitcnt vmcnt(8)
.Llw_up_s0:
	s_waitcnt lgkmcnt(0)
	s_barrier
	s_setprio 1
	v_mfma_f32_16x16x32_bf16 v[38:41], v[162:165], v[78:81], v[38:41]
	v_mfma_f32_16x16x32_bf16 v[34:37], v[178:181], v[78:81], v[34:37]
	v_mfma_f32_16x16x32_bf16 v[26:29], v[162:165], v[102:105], v[26:29]
	v_mfma_f32_16x16x32_bf16 v[18:21], v[178:181], v[102:105], v[18:21]
	v_mfma_f32_16x16x32_bf16 v[6:9], v[162:165], v[122:125], v[6:9]
	v_mfma_f32_16x16x32_bf16 v[2:5], v[178:181], v[122:125], v[2:5]
	v_mfma_f32_16x16x32_bf16 v[106:109], v[162:165], v[190:193], v[106:109]
	v_mfma_f32_16x16x32_bf16 v[130:133], v[178:181], v[190:193], v[130:133]
	v_mfma_f32_16x16x32_bf16 v[38:41], v[174:177], v[92:95], v[38:41]
	v_mfma_f32_16x16x32_bf16 v[34:37], v[182:185], v[92:95], v[34:37]
	v_mfma_f32_16x16x32_bf16 v[26:29], v[174:177], v[118:121], v[26:29]
	v_mfma_f32_16x16x32_bf16 v[18:21], v[182:185], v[118:121], v[18:21]
	v_mfma_f32_16x16x32_bf16 v[6:9], v[174:177], v[186:189], v[6:9]
	v_mfma_f32_16x16x32_bf16 v[2:5], v[182:185], v[186:189], v[2:5]
	v_mfma_f32_16x16x32_bf16 v[106:109], v[174:177], v[194:197], v[106:109]
	v_mfma_f32_16x16x32_bf16 v[162:165], v[182:185], v[194:197], v[130:133]
	s_setprio 0
	s_setprio 1
	v_mfma_f32_16x16x32_bf16 v[46:49], v[138:141], v[78:81], v[46:49]
	v_mfma_f32_16x16x32_bf16 v[42:45], v[166:169], v[78:81], v[42:45]
	v_mfma_f32_16x16x32_bf16 v[78:81], v[138:141], v[190:193], v[114:117]
	v_mfma_f32_16x16x32_bf16 v[30:33], v[138:141], v[102:105], v[30:33]
	v_mfma_f32_16x16x32_bf16 v[22:25], v[166:169], v[102:105], v[22:25]
	v_mfma_f32_16x16x32_bf16 v[14:17], v[138:141], v[122:125], v[14:17]
	v_mfma_f32_16x16x32_bf16 v[10:13], v[166:169], v[122:125], v[10:13]
	v_mfma_f32_16x16x32_bf16 v[114:117], v[142:145], v[194:197], v[78:81]
	v_mfma_f32_16x16x32_bf16 v[78:81], v[166:169], v[190:193], v[134:137]
	v_mfma_f32_16x16x32_bf16 v[46:49], v[142:145], v[92:95], v[46:49]
	v_mfma_f32_16x16x32_bf16 v[42:45], v[170:173], v[92:95], v[42:45]
	v_mfma_f32_16x16x32_bf16 v[30:33], v[142:145], v[118:121], v[30:33]
	v_mfma_f32_16x16x32_bf16 v[22:25], v[170:173], v[118:121], v[22:25]
	v_mfma_f32_16x16x32_bf16 v[14:17], v[142:145], v[186:189], v[14:17]
	v_mfma_f32_16x16x32_bf16 v[10:13], v[170:173], v[186:189], v[10:13]
	v_mfma_f32_16x16x32_bf16 v[166:169], v[170:173], v[194:197], v[78:81]
	s_setprio 0
	s_cmp_eq_u32 s18, 0
	s_cbranch_scc1 .Llw_up_m0
	s_waitcnt vmcnt(8)
; #define PG8_STAGE(bufoff, gbase, voff) glds16s2((voff)[0], (voff)[1], (const void*)(gbase), ldsn + (unsigned)(bufoff))
; #define PG8_LDA(dst, b, h) do { _Pragma("unroll") for (int m = 0; m < 4; ++m) _Pragma("unroll") for (int k = 0; k < 2; ++k) dst[m][k] = *(const LAS bf16x8*)(lds + PG8_SA(b, h) + aoff + m * 2048 + k * 1024); } while (0)
; #define PG8_LDB(dst, b, h) do { _Pragma("unroll") for (int n = 0; n < 2; ++n) _Pragma("unroll") for (int k = 0; k < 2; ++k) dst[n][k] = *(const LAS bf16x8*)(lds + PG8_SB(b, h) + boff + n * 2048 + k * 1024); } while (0)
; #define PG8_MMA(ai, bj, At, Bt) do { __builtin_amdgcn_s_setprio(1); _Pragma("unroll") for (int m = 0; m < 4; ++m) _Pragma("unroll") for (int n = 0; n < 2; ++n) _Pragma("unroll") for (int k = 0; k < 2; ++k) \
;         acc[ai][bj][m][n] = __builtin_amdgcn_mfma_f32_16x16x32_bf16(Bt[n][k], At[m][k], acc[ai][bj][m][n], 0, 0, 0); __builtin_amdgcn_s_setprio(0); } while (0)
; #define PG8_WAIT_V(n) asm volatile("s_waitcnt vmcnt(" #n ")" ::: "memory")
; #define PG8_WAIT_L(n) asm volatile("s_waitcnt lgkmcnt(" #n ")" ::: "memory")
; #define PG8_BAR __builtin_amdgcn_s_barrier()
; #define PG8_SCHED __builtin_amdgcn_sched_barrier(0)
; template <class Epi, bool ALIGN_EPI, bool EARLY_DRAIN = true, class Pre = NoPre>
; __device__ __forceinline__ void gemm_phase(LAS unsigned char* lds, const Gemm g, const StaticOrder& S, const Epi& E, int wv, const Pre& pre = Pre()) {
;     ...
;             const bool last = (t == nt - 2);
;             const char* a1 = cA + (size_t)(t + 1) * kstep;
;             const char* a2 = last ? nA : cA + (size_t)(t + 2) * kstep; const char* b2 = last ? nB : cB + (size_t)(t + 2) * kstep;
;             const char* a3 = a2 + kstep; const char* b3 = b2 + kstep;
;             int lf_ = EARLY_DRAIN ? __builtin_amdgcn_readfirstlane(landed_flag) : landed_flag; if constexpr (EARLY_DRAIN) asm volatile("" : "+s"(lf_)); landed_flag = 0;
;             PG8_LDB(B0, 0, 0); PG8_LDB(B1, 0, 1); PG8_SCHED; PG8_LDA(At, 0, 0); PG8_STAGE(PG8_SA(1, 1), a1 + ahs, voffA);
;             if (!lf_) PG8_WAIT_V(8);
;             PG8_WAIT_L(0); PG8_BAR; PG8_MMA(0, 0, At, B0); PG8_MMA(0, 1, At, B1); PG8_BAR; PG8_SCHED;
.Llw_up_m0:
	s_barrier
	s_add_i32 s0, s0, 2
	s_add_u32 s51, s51, 0x100
	s_addc_u32 s52, s52, 0
	s_add_u32 s53, s53, 0x100
	s_addc_u32 s61, s61, 0
	s_add_u32 s42, s42, 0x100
	s_addc_u32 s43, s43, 0
	s_cmp_gt_u32 s0, 13
	s_cbranch_scc1 .LBB0_565
.LBB0_559:
	ds_read_b128 v[130:133], v0
	ds_read_b128 v[174:177], v0 offset:1024
	ds_read_b128 v[178:181], v0 offset:2048
	ds_read_b128 v[182:185], v0 offset:3072
	ds_read_b128 v[134:137], v234
	ds_read_b128 v[138:141], v234 offset:1024
	ds_read_b128 v[142:145], v234 offset:2048
	ds_read_b128 v[170:173], v234 offset:3072
	ds_read_b128 v[102:105], v245
	ds_read_b128 v[202:205], v245 offset:1024
	ds_read_b128 v[118:121], v245 offset:2048
	ds_read_b128 v[122:125], v245 offset:3072
	ds_read_b128 v[194:197], v245 offset:4096
	ds_read_b128 v[198:201], v245 offset:5120
	ds_read_b128 v[186:189], v245 offset:6144
	ds_read_b128 v[190:193], v245 offset:7168
	s_mov_b32 m0, s67
	s_nop 0
	global_load_lds_dwordx4 v250, s[42:43]
	s_add_u32 m0, m0, 0x2000
	s_nop 0
	global_load_lds_dwordx4 v246, s[42:43]
	s_cmp_lg_u32 s18, 0
	s_cbranch_scc1 .Llw_up_s1
	s_waitcnt vmcnt(8)
.Llw_up_s1:
.LBB0_561:
	s_waitcnt lgkmcnt(0)
	s_cmp_eq_u32 s0, 12
	s_cselect_b32 s87, s71, s52
	s_cselect_b32 s86, s70, s51
	s_cselect_b32 s85, s47, s61
	s_cselect_b32 s84, s50, s53
	s_barrier
	s_setprio 1
	v_mfma_f32_16x16x32_bf16 v[70:73], v[130:133], v[102:105], v[70:73]
	v_mfma_f32_16x16x32_bf16 v[78:81], v[178:181], v[102:105], v[146:149]
	v_mfma_f32_16x16x32_bf16 v[74:77], v[130:133], v[118:121], v[74:77]
	v_mfma_f32_16x16x32_bf16 v[92:95], v[178:181], v[118:121], v[150:153]
	v_mfma_f32_16x16x32_bf16 v[82:85], v[130:133], v[194:197], v[82:85]
	v_mfma_f32_16x16x32_bf16 v[66:69], v[178:181], v[194:197], v[66:69]
	v_mfma_f32_16x16x32_bf16 v[54:57], v[130:133], v[186:189], v[54:57]
	v_mfma_f32_16x16x32_bf16 v[50:53], v[178:181], v[186:189], v[50:53]
	v_mfma_f32_16x16x32_bf16 v[70:73], v[174:177], v[202:205], v[70:73]
	v_mfma_f32_16x16x32_bf16 v[78:81], v[182:185], v[202:205], v[78:81]
	v_mfma_f32_16x16x32_bf16 v[74:77], v[174:177], v[122:125], v[74:77]
	v_mfma_f32_16x16x32_bf16 v[92:95], v[182:185], v[122:125], v[92:95]
	v_mfma_f32_16x16x32_bf16 v[82:85], v[174:177], v[198:201], v[82:85]
	v_mfma_f32_16x16x32_bf16 v[66:69], v[182:185], v[198:201], v[66:69]
	v_mfma_f32_16x16x32_bf16 v[54:57], v[174:177], v[190:193], v[54:57]
	v_mfma_f32_16x16x32_bf16 v[50:53], v[182:185], v[190:193], v[50:53]
	s_setprio 0
	s_setprio 1
	v_mfma_f32_16x16x32_bf16 v[96:99], v[134:137], v[118:121], v[98:101]
	v_mfma_f32_16x16x32_bf16 v[118:121], v[142:145], v[118:121], v[158:161]
	v_mfma_f32_16x16x32_bf16 v[86:89], v[134:137], v[102:105], v[88:91]
	v_mfma_f32_16x16x32_bf16 v[102:105], v[142:145], v[102:105], v[154:157]
	v_mfma_f32_16x16x32_bf16 v[96:99], v[138:141], v[122:125], v[96:99]
	v_mfma_f32_16x16x32_bf16 v[118:121], v[170:173], v[122:125], v[118:121]
	v_mfma_f32_16x16x32_bf16 v[122:125], v[134:137], v[194:197], v[126:129]
	v_mfma_f32_16x16x32_bf16 v[110:113], v[142:145], v[194:197], v[110:113]
	v_mfma_f32_16x16x32_bf16 v[62:65], v[134:137], v[186:189], v[62:65]
	v_mfma_f32_16x16x32_bf16 v[58:61], v[142:145], v[186:189], v[58:61]
	v_mfma_f32_16x16x32_bf16 v[86:89], v[138:141], v[202:205], v[86:89]
	v_mfma_f32_16x16x32_bf16 v[102:105], v[170:173], v[202:205], v[102:105]
	v_mfma_f32_16x16x32_bf16 v[122:125], v[138:141], v[198:201], v[122:125]
	v_mfma_f32_16x16x32_bf16 v[110:113], v[170:173], v[198:201], v[110:113]
	v_mfma_f32_16x16x32_bf16 v[62:65], v[138:141], v[190:193], v[62:65]
	v_mfma_f32_16x16x32_bf16 v[58:61], v[170:173], v[190:193], v[58:61]
	s_setprio 0
	s_cmp_eq_u32 s18, 0
	s_cbranch_scc1 .Llw_up_m1
	s_waitcnt vmcnt(8)
; #define PG8_STAGE(bufoff, gbase, voff) glds16s2((voff)[0], (voff)[1], (const void*)(gbase), ldsn + (unsigned)(bufoff))
; #define PG8_LDA(dst, b, h) do { _Pragma("unroll") for (int m = 0; m < 4; ++m) _Pragma("unroll") for (int k = 0; k < 2; ++k) dst[m][k] = *(const LAS bf16x8*)(lds + PG8_SA(b, h) + aoff + m * 2048 + k * 1024); } while (0)
; #define PG8_LDB(dst, b, h) do { _Pragma("unroll") for (int n = 0; n < 2; ++n) _Pragma("unroll") for (int k = 0; k < 2; ++k) dst[n][k] = *(const LAS bf16x8*)(lds + PG8_SB(b, h) + boff + n * 2048 + k * 1024); } while (0)
; #define PG8_MMA(ai, bj, At, Bt) do { __builtin_amdgcn_s_setprio(1); _Pragma("unroll") for (int m = 0; m < 4; ++m) _Pragma("unroll") for (int n = 0; n < 2; ++n) _Pragma("unroll") for (int k = 0; k < 2; ++k) \
;         acc[ai][bj][m][n] = __builtin_amdgcn_mfma_f32_16x16x32_bf16(Bt[n][k], At[m][k], acc[ai][bj][m][n], 0, 0, 0); __builtin_amdgcn_s_setprio(0); } while (0)
; #define PG8_WAIT_V(n) asm volatile("s_waitcnt vmcnt(" #n ")" ::: "memory")
; #define PG8_WAIT_L(n) asm volatile("s_waitcnt lgkmcnt(" #n ")" ::: "memory")
; #define PG8_BAR __builtin_amdgcn_s_barrier()
; #define PG8_SCHED __builtin_amdgcn_sched_barrier(0)
; template <class Epi, bool ALIGN_EPI, bool EARLY_DRAIN = true, class Pre = NoPre>
; __device__ __forceinline__ void gemm_phase(LAS unsigned char* lds, const Gemm g, const StaticOrder& S, const Epi& E, int wv, const Pre& pre = Pre()) {
;     ...
;             PG8_LDA(At, 0, 1); PG8_STAGE(PG8_SB(0, 0), b2, voffB); PG8_STAGE(PG8_SB(0, 1), b2 + bhs, voffB); PG8_STAGE(PG8_SA(0, 0), a2, voffA);
;             if (!lf_) PG8_WAIT_V(8);
;             PG8_WAIT_L(0); PG8_BAR; PG8_MMA(1, 0, At, B0); PG8_MMA(1, 1, At, B1); PG8_BAR; PG8_SCHED;
;             PG8_LDB(B0, 1, 0); PG8_LDB(B1, 1, 1); PG8_SCHED; PG8_LDA(At, 1, 0); PG8_STAGE(PG8_SA(0, 1), a2 + ahs, voffA);
;             if (!lf_) PG8_WAIT_V(8);
;             PG8_WAIT_L(0); PG8_BAR; PG8_MMA(0, 0, At, B0); PG8_MMA(0, 1, At, B1); PG8_BAR; PG8_SCHED;
;             PG8_LDA(At, 1, 1); PG8_STAGE(PG8_SB(1, 0), b3, voffB); PG8_STAGE(PG8_SB(1, 1), b3 + bhs, voffB); PG8_STAGE(PG8_SA(1, 0), a3, voffA);
.Llw_up_m1:
	s_barrier
	ds_read_b128 v[190:193], v245 offset:16384
	ds_read_b128 v[194:197], v245 offset:17408
	ds_read_b128 v[158:161], v245 offset:18432
	ds_read_b128 v[186:189], v245 offset:19456
	ds_read_b128 v[150:153], v245 offset:20480
	ds_read_b128 v[154:157], v245 offset:21504
	ds_read_b128 v[126:129], v245 offset:22528
	ds_read_b128 v[146:149], v245 offset:23552
	s_mov_b32 m0, s22
	s_nop 0
	global_load_lds_dwordx4 v251, s[84:85]
	s_add_u32 m0, m0, 0x2000
	s_nop 0
	global_load_lds_dwordx4 v247, s[84:85]
	s_add_u32 s14, s84, 0x580000
	s_addc_u32 s15, s85, 0
	s_mov_b32 m0, s23
	s_nop 0
	global_load_lds_dwordx4 v251, s[14:15]
	s_add_u32 m0, m0, 0x2000
	s_nop 0
	global_load_lds_dwordx4 v247, s[14:15]
	s_mov_b32 m0, s13
	s_nop 0
	global_load_lds_dwordx4 v250, s[86:87]
	s_add_u32 m0, m0, 0x2000
	s_nop 0
	global_load_lds_dwordx4 v246, s[86:87]
	s_cmp_lg_u32 s18, 0
	s_cbranch_scc1 .Llw_up_s2
	s_waitcnt vmcnt(8)
.Llw_up_s2:
.LBB0_563:
	s_waitcnt lgkmcnt(0)
	s_barrier
	s_setprio 1
	v_mfma_f32_16x16x32_bf16 v[38:41], v[130:133], v[190:193], v[38:41]
	v_mfma_f32_16x16x32_bf16 v[34:37], v[178:181], v[190:193], v[34:37]
	v_mfma_f32_16x16x32_bf16 v[26:29], v[130:133], v[158:161], v[26:29]
	v_mfma_f32_16x16x32_bf16 v[18:21], v[178:181], v[158:161], v[18:21]
	v_mfma_f32_16x16x32_bf16 v[6:9], v[130:133], v[150:153], v[6:9]
	v_mfma_f32_16x16x32_bf16 v[2:5], v[178:181], v[150:153], v[2:5]
	v_mfma_f32_16x16x32_bf16 v[106:109], v[130:133], v[126:129], v[106:109]
	v_mfma_f32_16x16x32_bf16 v[130:133], v[178:181], v[126:129], v[162:165]
	v_mfma_f32_16x16x32_bf16 v[38:41], v[174:177], v[194:197], v[38:41]
	v_mfma_f32_16x16x32_bf16 v[34:37], v[182:185], v[194:197], v[34:37]
	v_mfma_f32_16x16x32_bf16 v[26:29], v[174:177], v[186:189], v[26:29]
	v_mfma_f32_16x16x32_bf16 v[18:21], v[182:185], v[186:189], v[18:21]
	v_mfma_f32_16x16x32_bf16 v[6:9], v[174:177], v[154:157], v[6:9]
	v_mfma_f32_16x16x32_bf16 v[2:5], v[182:185], v[154:157], v[2:5]
	v_mfma_f32_16x16x32_bf16 v[106:109], v[174:177], v[146:149], v[106:109]
	v_mfma_f32_16x16x32_bf16 v[130:133], v[182:185], v[146:149], v[130:133]
	s_setprio 0
	s_setprio 1
	v_mfma_f32_16x16x32_bf16 v[46:49], v[134:137], v[190:193], v[46:49]
	v_mfma_f32_16x16x32_bf16 v[42:45], v[142:145], v[190:193], v[42:45]
	v_mfma_f32_16x16x32_bf16 v[30:33], v[134:137], v[158:161], v[30:33]
	v_mfma_f32_16x16x32_bf16 v[22:25], v[142:145], v[158:161], v[22:25]
	v_mfma_f32_16x16x32_bf16 v[14:17], v[134:137], v[150:153], v[14:17]
	v_mfma_f32_16x16x32_bf16 v[10:13], v[142:145], v[150:153], v[10:13]
	v_mfma_f32_16x16x32_bf16 v[114:117], v[134:137], v[126:129], v[114:117]
	v_mfma_f32_16x16x32_bf16 v[126:129], v[142:145], v[126:129], v[166:169]
	v_mfma_f32_16x16x32_bf16 v[46:49], v[138:141], v[194:197], v[46:49]
	v_mfma_f32_16x16x32_bf16 v[42:45], v[170:173], v[194:197], v[42:45]
	v_mfma_f32_16x16x32_bf16 v[30:33], v[138:141], v[186:189], v[30:33]
	v_mfma_f32_16x16x32_bf16 v[22:25], v[170:173], v[186:189], v[22:25]
	v_mfma_f32_16x16x32_bf16 v[14:17], v[138:141], v[154:157], v[14:17]
	v_mfma_f32_16x16x32_bf16 v[10:13], v[170:173], v[154:157], v[10:13]
	v_mfma_f32_16x16x32_bf16 v[114:117], v[138:141], v[146:149], v[114:117]
	v_mfma_f32_16x16x32_bf16 v[134:137], v[170:173], v[146:149], v[126:129]
	s_setprio 0
	s_cmp_eq_u32 s18, 0
	s_cbranch_scc1 .Llw_up_m2
	s_waitcnt vmcnt(8)
.Llw_up_m2:
	s_barrier
	ds_read_b128 v[162:165], v235
	ds_read_b128 v[174:177], v235 offset:1024
	ds_read_b128 v[178:181], v235 offset:2048
	ds_read_b128 v[182:185], v235 offset:3072
	ds_read_b128 v[138:141], v248
	ds_read_b128 v[142:145], v248 offset:1024
	ds_read_b128 v[166:169], v248 offset:2048
	ds_read_b128 v[170:173], v248 offset:3072
	ds_read_b128 v[154:157], v245 offset:32768
	ds_read_b128 v[202:205], v245 offset:33792
	ds_read_b128 v[126:129], v245 offset:34816
	ds_read_b128 v[158:161], v245 offset:35840
	ds_read_b128 v[194:197], v245 offset:36864
	ds_read_b128 v[198:201], v245 offset:37888
	ds_read_b128 v[186:189], v245 offset:38912
	ds_read_b128 v[190:193], v245 offset:39936
	s_add_u32 s14, s86, 0x2000
	s_addc_u32 s15, s87, 0
	s_mov_b32 m0, s45
	s_nop 0
	global_load_lds_dwordx4 v250, s[14:15]
	s_add_u32 m0, m0, 0x2000
	s_nop 0
	global_load_lds_dwordx4 v246, s[14:15]
	s_cmp_lg_u32 s18, 0
	s_cbranch_scc1 .Llw_up_s3
	s_waitcnt vmcnt(8)
.Llw_up_s3:
	s_branch .LBB0_558
	s_nop 0
	s_nop 0
	s_nop 0
	s_nop 0
	s_nop 0
	s_nop 0
	s_nop 0
	s_nop 0
	s_nop 0
	s_nop 0
	s_nop 0
	s_nop 0
	s_nop 0
